# down-proj epilogue: second half's residual loads issued as soon as their registers free up during the first half (group 0 fully early via spare registers); vmcnt waits regenerated
# baseline (speedup 1.0000x reference)
; __device__ __forceinline__ unsigned pk2(float lo, float hi) { const f32x2_t v = {lo, hi}; const bf16x2_t b = __builtin_convertvector(v, bf16x2_t); return __builtin_bit_cast(unsigned, b); }
;     __device__ __forceinline__ void operator()(const f32x4 (&acc)[2][2][4][2], const Unit& u, int wr, int wc, int fr, int fq) const {
;     ...
;         for (int ai = 0; ai < 2; ++ai) {
;             f32x4 bv[4][2][2];
; #pragma unroll
;             for (int m = 0; m < 4; ++m)
; #pragma unroll
;                 for (int bj = 0; bj < 2; ++bj)
; #pragma unroll
;                     for (int n = 0; n < 2; ++n) bv[m][bj][n] = *(const f32x4*)(base + (size_t)(row0 + ai * 128 + m * 16) * D + col0 + bj * 128 + n * 16);
;             asm volatile("" ::: "memory");
; #pragma unroll
;             for (int m = 0; m < 4; ++m) {
;                 const int row = row0 + ai * 128 + m * 16; float s = 0.f;
; #pragma unroll
;                 for (int bj = 0; bj < 2; ++bj)
; #pragma unroll
;                     for (int n = 0; n < 2; ++n) {
;                         const size_t off = (size_t)row * D + col0 + bj * 128 + n * 16;
;                         const f32x4 v = bv[m][bj][n] + acc[ai][bj][m][n] * alpha;
;                         *(f32x4*)(out + off) = v; s += (v[0] * v[0] + v[1] * v[1]) + (v[2] * v[2] + v[3] * v[3]);
;                         if (xb) { v2u w; w.x = pk2(v[0], v[1]); w.y = pk2(v[2], v[3]); *(v2u*)(xb + off) = w; }
;                     }
;                 s += __shfl_xor(s, 16); s += __shfl_xor(s, 32);
;                 if (fq == 0) atomicAdd(ss + row, s);
.LBB0_320:
	s_or_b64 exec, exec, s[26:27]
	v_add_u32_e32 v238, 0x80, v192
	v_ashrrev_i32_e32 v239, 31, v238
	v_lshlrev_b64 v[238:239], 12, v[238:239]
	v_lshl_add_u64 v[240:241], v[190:191], 0, v[238:239]
	global_load_dwordx4 v[120:123], v[240:241], off
	global_load_dwordx4 v[124:127], v[240:241], off offset:64
	global_load_dwordx4 v[246:249], v[240:241], off offset:512
	global_load_dwordx4 v[250:253], v[240:241], off offset:576
	s_waitcnt lgkmcnt(0)
	v_lshlrev_b64 v[112:113], 10, v[198:199]
	v_lshl_add_u64 v[112:113], v[112:113], 0, v[188:189]
	v_pk_fma_f32 v[110:111], v[110:111], 0.5, v[174:175] op_sel_hi:[1,0,1]
	v_pk_fma_f32 v[108:109], v[108:109], 0.5, v[172:173] op_sel_hi:[1,0,1]
	v_lshl_add_u64 v[114:115], v[112:113], 2, s[14:15]
	v_mul_f32_e32 v116, v109, v109
	v_mul_f32_e32 v117, v111, v111
	global_store_dwordx4 v[114:115], v[108:111], off
	v_fmac_f32_e32 v116, v108, v108
	v_fmac_f32_e32 v117, v110, v110
	v_cvt_pk_bf16_f32 v108, v108, v109
	v_cvt_pk_bf16_f32 v109, v110, v111
	v_lshlrev_b64 v[110:111], 1, v[112:113]
	v_lshl_add_u64 v[112:113], s[56:57], 0, v[110:111]
	v_pk_fma_f32 v[106:107], v[106:107], 0.5, v[170:171] op_sel_hi:[1,0,1]
	v_pk_fma_f32 v[104:105], v[104:105], 0.5, v[168:169] op_sel_hi:[1,0,1]
	global_store_dwordx2 v[112:113], v[108:109], off
	v_mul_f32_e32 v108, v105, v105
	v_mul_f32_e32 v109, v107, v107
	global_store_dwordx4 v[114:115], v[104:107], off offset:64
	v_fmac_f32_e32 v108, v104, v104
	v_fmac_f32_e32 v109, v106, v106
	v_cvt_pk_bf16_f32 v104, v104, v105
	v_cvt_pk_bf16_f32 v105, v106, v107
	v_or_b32_e32 v106, 32, v110
	v_mov_b32_e32 v107, v111
	v_lshl_add_u64 v[106:107], s[56:57], 0, v[106:107]
	v_pk_fma_f32 v[102:103], v[102:103], 0.5, v[166:167] op_sel_hi:[1,0,1]
	v_pk_fma_f32 v[100:101], v[100:101], 0.5, v[164:165] op_sel_hi:[1,0,1]
	global_store_dwordx2 v[106:107], v[104:105], off
	v_mul_f32_e32 v104, v101, v101
	v_mul_f32_e32 v105, v103, v103
	v_fmac_f32_e32 v104, v100, v100
	v_fmac_f32_e32 v105, v102, v102
	v_pk_fma_f32 v[98:99], v[98:99], 0.5, v[162:163] op_sel_hi:[1,0,1]
	v_pk_fma_f32 v[96:97], v[96:97], 0.5, v[160:161] op_sel_hi:[1,0,1]
	v_add_f32_e32 v116, v116, v117
	v_add_f32_e32 v108, v108, v109
	v_add_f32_e32 v104, v104, v105
	v_mul_f32_e32 v105, v97, v97
	v_mul_f32_e32 v106, v99, v99
	v_add_f32_e32 v108, v116, v108
	v_fmac_f32_e32 v105, v96, v96
	v_fmac_f32_e32 v106, v98, v98
	v_add_f32_e32 v104, v108, v104
	v_add_f32_e32 v105, v105, v106
	v_add_f32_e32 v104, v104, v105
	ds_bpermute_b32 v105, v210, v104
	global_store_dwordx4 v[114:115], v[100:103], off offset:512
	s_nop 1
	v_cvt_pk_bf16_f32 v100, v100, v101
	v_cvt_pk_bf16_f32 v101, v102, v103
	v_or_b32_e32 v102, 0x100, v110
	v_mov_b32_e32 v103, v111
	v_lshl_add_u64 v[102:103], s[56:57], 0, v[102:103]
	global_store_dwordx2 v[102:103], v[100:101], off
	global_store_dwordx4 v[114:115], v[96:99], off offset:576
	v_cvt_pk_bf16_f32 v100, v96, v97
	v_or_b32_e32 v110, 0x120, v110
	s_waitcnt lgkmcnt(0)
	v_add_f32_e32 v96, v104, v105
	ds_bpermute_b32 v97, v209, v96
	v_cvt_pk_bf16_f32 v101, v98, v99
	v_lshl_add_u64 v[98:99], s[56:57], 0, v[110:111]
	global_store_dwordx2 v[98:99], v[100:101], off
	s_and_saveexec_b64 s[26:27], s[4:5]
	s_cbranch_execz .LBB0_322
	v_lshl_add_u64 v[98:99], v[198:199], 2, s[18:19]
	s_waitcnt lgkmcnt(0)
	v_add_f32_e32 v96, v96, v97
	global_atomic_add_f32 v[98:99], v96, off
.LBB0_322:
	s_or_b64 exec, exec, s[26:27]
	v_add_u32_e32 v238, 0x90, v192
	v_ashrrev_i32_e32 v239, 31, v238
	v_lshlrev_b64 v[238:239], 12, v[238:239]
	v_lshl_add_u64 v[242:243], v[190:191], 0, v[238:239]
	global_load_dwordx4 v[108:111], v[242:243], off
	global_load_dwordx4 v[104:107], v[242:243], off offset:64
	s_waitcnt lgkmcnt(0)
	v_lshlrev_b64 v[96:97], 10, v[196:197]
	v_lshl_add_u64 v[96:97], v[96:97], 0, v[188:189]
	v_pk_fma_f32 v[94:95], v[94:95], 0.5, v[158:159] op_sel_hi:[1,0,1]
	v_pk_fma_f32 v[92:93], v[92:93], 0.5, v[156:157] op_sel_hi:[1,0,1]
	v_lshl_add_u64 v[98:99], v[96:97], 2, s[14:15]
	v_mul_f32_e32 v100, v93, v93
	v_mul_f32_e32 v101, v95, v95
	global_store_dwordx4 v[98:99], v[92:95], off
	v_fmac_f32_e32 v100, v92, v92
	v_fmac_f32_e32 v101, v94, v94
	v_cvt_pk_bf16_f32 v92, v92, v93
	v_cvt_pk_bf16_f32 v93, v94, v95
	v_lshlrev_b64 v[94:95], 1, v[96:97]
	v_lshl_add_u64 v[96:97], s[56:57], 0, v[94:95]
	v_pk_fma_f32 v[90:91], v[90:91], 0.5, v[154:155] op_sel_hi:[1,0,1]
	v_pk_fma_f32 v[88:89], v[88:89], 0.5, v[152:153] op_sel_hi:[1,0,1]
	global_store_dwordx2 v[96:97], v[92:93], off
	v_mul_f32_e32 v92, v89, v89
	v_mul_f32_e32 v93, v91, v91
	global_store_dwordx4 v[98:99], v[88:91], off offset:64
	v_fmac_f32_e32 v92, v88, v88
	v_fmac_f32_e32 v93, v90, v90
	v_cvt_pk_bf16_f32 v88, v88, v89
	v_cvt_pk_bf16_f32 v89, v90, v91
	v_or_b32_e32 v90, 32, v94
	v_mov_b32_e32 v91, v95
	v_lshl_add_u64 v[90:91], s[56:57], 0, v[90:91]
	v_pk_fma_f32 v[86:87], v[86:87], 0.5, v[150:151] op_sel_hi:[1,0,1]
	v_pk_fma_f32 v[84:85], v[84:85], 0.5, v[148:149] op_sel_hi:[1,0,1]
	global_store_dwordx2 v[90:91], v[88:89], off
	v_mul_f32_e32 v88, v85, v85
	v_mul_f32_e32 v89, v87, v87
	v_fmac_f32_e32 v88, v84, v84
	v_fmac_f32_e32 v89, v86, v86
	v_pk_fma_f32 v[82:83], v[82:83], 0.5, v[146:147] op_sel_hi:[1,0,1]
	v_pk_fma_f32 v[80:81], v[80:81], 0.5, v[144:145] op_sel_hi:[1,0,1]
	v_add_f32_e32 v100, v100, v101
	v_add_f32_e32 v92, v92, v93
	v_add_f32_e32 v88, v88, v89
	v_mul_f32_e32 v89, v81, v81
	v_mul_f32_e32 v90, v83, v83
	v_add_f32_e32 v92, v100, v92
	v_fmac_f32_e32 v89, v80, v80
	v_fmac_f32_e32 v90, v82, v82
	v_add_f32_e32 v88, v92, v88
	v_add_f32_e32 v89, v89, v90
	v_add_f32_e32 v88, v88, v89
	ds_bpermute_b32 v89, v210, v88
	global_store_dwordx4 v[98:99], v[84:87], off offset:512
	s_nop 1
	v_cvt_pk_bf16_f32 v84, v84, v85
	v_cvt_pk_bf16_f32 v85, v86, v87
	v_or_b32_e32 v86, 0x100, v94
	v_mov_b32_e32 v87, v95
	v_lshl_add_u64 v[86:87], s[56:57], 0, v[86:87]
	global_store_dwordx2 v[86:87], v[84:85], off
	global_store_dwordx4 v[98:99], v[80:83], off offset:576
	v_cvt_pk_bf16_f32 v84, v80, v81
	v_or_b32_e32 v94, 0x120, v94
	s_waitcnt lgkmcnt(0)
	v_add_f32_e32 v80, v88, v89
	ds_bpermute_b32 v81, v209, v80
	v_cvt_pk_bf16_f32 v85, v82, v83
	v_lshl_add_u64 v[82:83], s[56:57], 0, v[94:95]
	global_store_dwordx2 v[82:83], v[84:85], off
	s_and_saveexec_b64 s[26:27], s[4:5]
	s_cbranch_execz .LBB0_324
	v_lshl_add_u64 v[82:83], v[196:197], 2, s[18:19]
	s_waitcnt lgkmcnt(0)
	v_add_f32_e32 v80, v80, v81
	global_atomic_add_f32 v[82:83], v80, off
; __device__ __forceinline__ unsigned pk2(float lo, float hi) { const f32x2_t v = {lo, hi}; const bf16x2_t b = __builtin_convertvector(v, bf16x2_t); return __builtin_bit_cast(unsigned, b); }
;     __device__ __forceinline__ void operator()(const f32x4 (&acc)[2][2][4][2], const Unit& u, int wr, int wc, int fr, int fq) const {
;     ...
;         for (int ai = 0; ai < 2; ++ai) {
;             f32x4 bv[4][2][2];
; #pragma unroll
;             for (int m = 0; m < 4; ++m)
; #pragma unroll
;                 for (int bj = 0; bj < 2; ++bj)
; #pragma unroll
;                     for (int n = 0; n < 2; ++n) bv[m][bj][n] = *(const f32x4*)(base + (size_t)(row0 + ai * 128 + m * 16) * D + col0 + bj * 128 + n * 16);
;             asm volatile("" ::: "memory");
; #pragma unroll
;             for (int m = 0; m < 4; ++m) {
;                 const int row = row0 + ai * 128 + m * 16; float s = 0.f;
; #pragma unroll
;                 for (int bj = 0; bj < 2; ++bj)
; #pragma unroll
;                     for (int n = 0; n < 2; ++n) {
;                         const size_t off = (size_t)row * D + col0 + bj * 128 + n * 16;
;                         const f32x4 v = bv[m][bj][n] + acc[ai][bj][m][n] * alpha;
;                         *(f32x4*)(out + off) = v; s += (v[0] * v[0] + v[1] * v[1]) + (v[2] * v[2] + v[3] * v[3]);
;                         if (xb) { v2u w; w.x = pk2(v[0], v[1]); w.y = pk2(v[2], v[3]); *(v2u*)(xb + off) = w; }
;                     }
;                 s += __shfl_xor(s, 16); s += __shfl_xor(s, 32);
;                 if (fq == 0) atomicAdd(ss + row, s);
.LBB0_324:
	s_or_b64 exec, exec, s[26:27]
	v_add_u32_e32 v238, 0x90, v192
	v_ashrrev_i32_e32 v239, 31, v238
	v_lshlrev_b64 v[238:239], 12, v[238:239]
	v_lshl_add_u64 v[242:243], v[190:191], 0, v[238:239]
	global_load_dwordx4 v[100:103], v[242:243], off offset:512
	global_load_dwordx4 v[96:99], v[242:243], off offset:576
	v_add_u32_e32 v238, 0xa0, v192
	v_ashrrev_i32_e32 v239, 31, v238
	v_lshlrev_b64 v[238:239], 12, v[238:239]
	v_lshl_add_u64 v[244:245], v[190:191], 0, v[238:239]
	global_load_dwordx4 v[92:95], v[244:245], off
	global_load_dwordx4 v[88:91], v[244:245], off offset:64
	s_waitcnt lgkmcnt(0)
	v_lshlrev_b64 v[80:81], 10, v[194:195]
	v_lshl_add_u64 v[80:81], v[80:81], 0, v[188:189]
	v_pk_fma_f32 v[78:79], v[78:79], 0.5, v[142:143] op_sel_hi:[1,0,1]
	v_pk_fma_f32 v[76:77], v[76:77], 0.5, v[140:141] op_sel_hi:[1,0,1]
	v_lshl_add_u64 v[82:83], v[80:81], 2, s[14:15]
	v_mul_f32_e32 v84, v77, v77
	v_mul_f32_e32 v85, v79, v79
	global_store_dwordx4 v[82:83], v[76:79], off
	v_fmac_f32_e32 v84, v76, v76
	v_fmac_f32_e32 v85, v78, v78
	v_cvt_pk_bf16_f32 v76, v76, v77
	v_cvt_pk_bf16_f32 v77, v78, v79
	v_lshlrev_b64 v[78:79], 1, v[80:81]
	v_lshl_add_u64 v[80:81], s[56:57], 0, v[78:79]
	v_pk_fma_f32 v[74:75], v[74:75], 0.5, v[138:139] op_sel_hi:[1,0,1]
	v_pk_fma_f32 v[72:73], v[72:73], 0.5, v[136:137] op_sel_hi:[1,0,1]
	global_store_dwordx2 v[80:81], v[76:77], off
	v_mul_f32_e32 v76, v73, v73
	v_mul_f32_e32 v77, v75, v75
	global_store_dwordx4 v[82:83], v[72:75], off offset:64
	v_fmac_f32_e32 v76, v72, v72
	v_fmac_f32_e32 v77, v74, v74
	v_cvt_pk_bf16_f32 v72, v72, v73
	v_cvt_pk_bf16_f32 v73, v74, v75
	v_or_b32_e32 v74, 32, v78
	v_mov_b32_e32 v75, v79
	v_lshl_add_u64 v[74:75], s[56:57], 0, v[74:75]
	v_pk_fma_f32 v[70:71], v[70:71], 0.5, v[134:135] op_sel_hi:[1,0,1]
	v_pk_fma_f32 v[68:69], v[68:69], 0.5, v[132:133] op_sel_hi:[1,0,1]
	global_store_dwordx2 v[74:75], v[72:73], off
	v_mul_f32_e32 v72, v69, v69
	v_mul_f32_e32 v73, v71, v71
	v_fmac_f32_e32 v72, v68, v68
	v_fmac_f32_e32 v73, v70, v70
	v_pk_fma_f32 v[66:67], v[66:67], 0.5, v[130:131] op_sel_hi:[1,0,1]
	v_pk_fma_f32 v[64:65], v[64:65], 0.5, v[128:129] op_sel_hi:[1,0,1]
	v_add_f32_e32 v84, v84, v85
	v_add_f32_e32 v76, v76, v77
	v_add_f32_e32 v72, v72, v73
	v_mul_f32_e32 v73, v65, v65
	v_mul_f32_e32 v74, v67, v67
	v_add_f32_e32 v76, v84, v76
	v_fmac_f32_e32 v73, v64, v64
	v_fmac_f32_e32 v74, v66, v66
	v_add_f32_e32 v72, v76, v72
	v_add_f32_e32 v73, v73, v74
	v_add_f32_e32 v72, v72, v73
	ds_bpermute_b32 v73, v210, v72
	global_store_dwordx4 v[82:83], v[68:71], off offset:512
	s_nop 1
	v_cvt_pk_bf16_f32 v68, v68, v69
	v_cvt_pk_bf16_f32 v69, v70, v71
	v_or_b32_e32 v70, 0x100, v78
	v_mov_b32_e32 v71, v79
	v_lshl_add_u64 v[70:71], s[56:57], 0, v[70:71]
	global_store_dwordx2 v[70:71], v[68:69], off
	global_store_dwordx4 v[82:83], v[64:67], off offset:576
	v_cvt_pk_bf16_f32 v68, v64, v65
	v_or_b32_e32 v78, 0x120, v78
	s_waitcnt lgkmcnt(0)
	v_add_f32_e32 v64, v72, v73
	ds_bpermute_b32 v65, v209, v64
	v_cvt_pk_bf16_f32 v69, v66, v67
	v_lshl_add_u64 v[66:67], s[56:57], 0, v[78:79]
	global_store_dwordx2 v[66:67], v[68:69], off
	s_and_saveexec_b64 s[26:27], s[4:5]
	s_cbranch_execz .LBB0_326
	v_lshl_add_u64 v[66:67], v[194:195], 2, s[18:19]
	s_waitcnt lgkmcnt(0)
	v_add_f32_e32 v64, v64, v65
	global_atomic_add_f32 v[66:67], v64, off
.LBB0_326:
	s_or_b64 exec, exec, s[26:27]
	v_add_u32_e32 v118, 0x80, v192
	v_ashrrev_i32_e32 v119, 31, v118
	s_waitcnt lgkmcnt(0)
	v_lshlrev_b64 v[64:65], 12, v[118:119]
	v_lshl_add_u64 v[64:65], v[190:191], 0, v[64:65]
	v_add_u32_e32 v116, 0x90, v192
	v_add_u32_e32 v114, 0xa0, v192
	v_add_u32_e32 v112, 0xb0, v192
	v_ashrrev_i32_e32 v117, 31, v116
	v_ashrrev_i32_e32 v115, 31, v114
	v_ashrrev_i32_e32 v113, 31, v112
	v_lshlrev_b64 v[64:65], 12, v[116:117]
	v_lshlrev_b64 v[66:67], 12, v[114:115]
	v_lshlrev_b64 v[68:69], 12, v[112:113]
	v_lshl_add_u64 v[64:65], v[190:191], 0, v[64:65]
	v_lshl_add_u64 v[66:67], v[190:191], 0, v[66:67]
	v_lshl_add_u64 v[136:137], v[190:191], 0, v[68:69]
	global_load_dwordx4 v[84:87], v[66:67], off offset:512
	global_load_dwordx4 v[80:83], v[66:67], off offset:576
	global_load_dwordx4 v[76:79], v[136:137], off
	global_load_dwordx4 v[72:75], v[136:137], off offset:64
	global_load_dwordx4 v[68:71], v[136:137], off offset:512
	s_nop 0
	global_load_dwordx4 v[64:67], v[136:137], off offset:576
	v_lshlrev_b64 v[136:137], 10, v[118:119]
	v_lshl_add_u64 v[136:137], v[136:137], 0, v[188:189]
	v_lshl_add_u64 v[138:139], v[136:137], 2, s[14:15]
	v_lshlrev_b64 v[136:137], 1, v[136:137]
	v_or_b32_e32 v142, 32, v136
	v_mov_b32_e32 v143, v137
	v_lshl_add_u64 v[140:141], s[56:57], 0, v[136:137]
	v_lshl_add_u64 v[142:143], s[56:57], 0, v[142:143]
	v_or_b32_e32 v144, 0x100, v136
	v_mov_b32_e32 v145, v137
	v_or_b32_e32 v136, 0x120, v136
	s_waitcnt vmcnt(39)
	v_pk_fma_f32 v[62:63], v[62:63], 0.5, v[122:123] op_sel_hi:[1,0,1]
	v_pk_fma_f32 v[60:61], v[60:61], 0.5, v[120:121] op_sel_hi:[1,0,1]
	s_waitcnt vmcnt(38)
	v_pk_fma_f32 v[58:59], v[58:59], 0.5, v[126:127] op_sel_hi:[1,0,1]
	v_pk_fma_f32 v[56:57], v[56:57], 0.5, v[124:125] op_sel_hi:[1,0,1]
	s_waitcnt vmcnt(37)
	v_pk_fma_f32 v[54:55], v[54:55], 0.5, v[248:249] op_sel_hi:[1,0,1]
	v_pk_fma_f32 v[52:53], v[52:53], 0.5, v[246:247] op_sel_hi:[1,0,1]
	global_store_dwordx4 v[138:139], v[60:63], off
	v_mul_f32_e32 v126, v61, v61
	v_mul_f32_e32 v127, v63, v63
	v_cvt_pk_bf16_f32 v120, v60, v61
	v_cvt_pk_bf16_f32 v121, v62, v63
	v_mul_f32_e32 v61, v57, v57
	v_mul_f32_e32 v63, v59, v59
	s_waitcnt vmcnt(37)
; __device__ __forceinline__ unsigned pk2(float lo, float hi) { const f32x2_t v = {lo, hi}; const bf16x2_t b = __builtin_convertvector(v, bf16x2_t); return __builtin_bit_cast(unsigned, b); }
;     __device__ __forceinline__ void operator()(const f32x4 (&acc)[2][2][4][2], const Unit& u, int wr, int wc, int fr, int fq) const {
;     ...
;         for (int ai = 0; ai < 2; ++ai) {
;             f32x4 bv[4][2][2];
; #pragma unroll
;             for (int m = 0; m < 4; ++m)
; #pragma unroll
;                 for (int bj = 0; bj < 2; ++bj)
; #pragma unroll
;                     for (int n = 0; n < 2; ++n) bv[m][bj][n] = *(const f32x4*)(base + (size_t)(row0 + ai * 128 + m * 16) * D + col0 + bj * 128 + n * 16);
;             asm volatile("" ::: "memory");
; #pragma unroll
;             for (int m = 0; m < 4; ++m) {
;                 const int row = row0 + ai * 128 + m * 16; float s = 0.f;
; #pragma unroll
;                 for (int bj = 0; bj < 2; ++bj)
; #pragma unroll
;                     for (int n = 0; n < 2; ++n) {
;                         const size_t off = (size_t)row * D + col0 + bj * 128 + n * 16;
;                         const f32x4 v = bv[m][bj][n] + acc[ai][bj][m][n] * alpha;
;                         *(f32x4*)(out + off) = v; s += (v[0] * v[0] + v[1] * v[1]) + (v[2] * v[2] + v[3] * v[3]);
;                         if (xb) { v2u w; w.x = pk2(v[0], v[1]); w.y = pk2(v[2], v[3]); *(v2u*)(xb + off) = w; }
;                     }
;                 s += __shfl_xor(s, 16); s += __shfl_xor(s, 32);
;                 if (fq == 0) atomicAdd(ss + row, s);
	v_pk_fma_f32 v[50:51], v[50:51], 0.5, v[252:253] op_sel_hi:[1,0,1]
	v_pk_fma_f32 v[48:49], v[48:49], 0.5, v[250:251] op_sel_hi:[1,0,1]
	v_cvt_pk_bf16_f32 v122, v56, v57
	v_cvt_pk_bf16_f32 v123, v58, v59
	v_mul_f32_e32 v128, v53, v53
	v_mul_f32_e32 v129, v55, v55
	v_fmac_f32_e32 v126, v60, v60
	v_fmac_f32_e32 v127, v62, v62
	v_fmac_f32_e32 v61, v56, v56
	v_fmac_f32_e32 v63, v58, v58
	v_cvt_pk_bf16_f32 v124, v52, v53
	v_mul_f32_e32 v130, v49, v49
	v_mul_f32_e32 v131, v51, v51
	global_store_dwordx2 v[140:141], v[120:121], off
	global_store_dwordx4 v[138:139], v[56:59], off offset:64
	global_store_dwordx2 v[142:143], v[122:123], off
	global_store_dwordx4 v[138:139], v[52:55], off offset:512
	v_fmac_f32_e32 v128, v52, v52
	v_fmac_f32_e32 v129, v54, v54
	v_add_f32_e32 v52, v126, v127
	v_add_f32_e32 v53, v61, v63
	v_cvt_pk_bf16_f32 v125, v54, v55
	v_fmac_f32_e32 v130, v48, v48
	v_fmac_f32_e32 v131, v50, v50
	v_add_f32_e32 v54, v128, v129
	v_add_f32_e32 v52, v52, v53
	v_add_f32_e32 v52, v52, v54
	v_add_f32_e32 v53, v130, v131
	v_add_f32_e32 v54, v52, v53
	ds_bpermute_b32 v55, v210, v54
	v_lshl_add_u64 v[52:53], s[56:57], 0, v[144:145]
	global_store_dwordx2 v[52:53], v[124:125], off
	global_store_dwordx4 v[138:139], v[48:51], off offset:576
	v_cvt_pk_bf16_f32 v52, v48, v49
	v_cvt_pk_bf16_f32 v53, v50, v51
	s_waitcnt lgkmcnt(0)
	v_add_f32_e32 v48, v54, v55
	ds_bpermute_b32 v49, v209, v48
	v_lshl_add_u64 v[50:51], s[56:57], 0, v[136:137]
	global_store_dwordx2 v[50:51], v[52:53], off
	s_and_saveexec_b64 s[26:27], s[4:5]
	s_cbranch_execz .LBB0_328
	v_lshl_add_u64 v[50:51], v[118:119], 2, s[18:19]
	s_waitcnt lgkmcnt(0)
	v_add_f32_e32 v48, v48, v49
	global_atomic_add_f32 v[50:51], v48, off
.LBB0_328:
	s_or_b64 exec, exec, s[26:27]
	s_waitcnt lgkmcnt(0)
	v_lshlrev_b64 v[48:49], 10, v[116:117]
	v_lshl_add_u64 v[48:49], v[48:49], 0, v[188:189]
	s_waitcnt vmcnt(35)
	v_pk_fma_f32 v[46:47], v[46:47], 0.5, v[110:111] op_sel_hi:[1,0,1]
	v_pk_fma_f32 v[44:45], v[44:45], 0.5, v[108:109] op_sel_hi:[1,0,1]
	v_lshl_add_u64 v[50:51], v[48:49], 2, s[14:15]
	v_mul_f32_e32 v52, v45, v45
	v_mul_f32_e32 v53, v47, v47
	global_store_dwordx4 v[50:51], v[44:47], off
	v_fmac_f32_e32 v52, v44, v44
	v_fmac_f32_e32 v53, v46, v46
	v_cvt_pk_bf16_f32 v44, v44, v45
	v_cvt_pk_bf16_f32 v45, v46, v47
	v_lshlrev_b64 v[46:47], 1, v[48:49]
	v_lshl_add_u64 v[48:49], s[56:57], 0, v[46:47]
	s_waitcnt vmcnt(35)
	v_pk_fma_f32 v[42:43], v[42:43], 0.5, v[106:107] op_sel_hi:[1,0,1]
	v_pk_fma_f32 v[40:41], v[40:41], 0.5, v[104:105] op_sel_hi:[1,0,1]
	global_store_dwordx2 v[48:49], v[44:45], off
	v_mul_f32_e32 v44, v41, v41
	v_mul_f32_e32 v45, v43, v43
	global_store_dwordx4 v[50:51], v[40:43], off offset:64
	v_fmac_f32_e32 v44, v40, v40
	v_fmac_f32_e32 v45, v42, v42
	v_cvt_pk_bf16_f32 v40, v40, v41
	v_cvt_pk_bf16_f32 v41, v42, v43
	v_or_b32_e32 v42, 32, v46
	v_mov_b32_e32 v43, v47
	v_lshl_add_u64 v[42:43], s[56:57], 0, v[42:43]
	s_waitcnt vmcnt(28)
	v_pk_fma_f32 v[38:39], v[38:39], 0.5, v[102:103] op_sel_hi:[1,0,1]
	v_pk_fma_f32 v[36:37], v[36:37], 0.5, v[100:101] op_sel_hi:[1,0,1]
	global_store_dwordx2 v[42:43], v[40:41], off
	v_mul_f32_e32 v40, v37, v37
	v_mul_f32_e32 v41, v39, v39
	v_fmac_f32_e32 v40, v36, v36
	v_fmac_f32_e32 v41, v38, v38
	s_waitcnt vmcnt(28)
	v_pk_fma_f32 v[34:35], v[34:35], 0.5, v[98:99] op_sel_hi:[1,0,1]
	v_pk_fma_f32 v[32:33], v[32:33], 0.5, v[96:97] op_sel_hi:[1,0,1]
	v_add_f32_e32 v52, v52, v53
	v_add_f32_e32 v44, v44, v45
	v_add_f32_e32 v40, v40, v41
	v_mul_f32_e32 v41, v33, v33
	v_mul_f32_e32 v42, v35, v35
	v_add_f32_e32 v44, v52, v44
	v_fmac_f32_e32 v41, v32, v32
	v_fmac_f32_e32 v42, v34, v34
	v_add_f32_e32 v40, v44, v40
	v_add_f32_e32 v41, v41, v42
	v_add_f32_e32 v40, v40, v41
	ds_bpermute_b32 v41, v210, v40
	global_store_dwordx4 v[50:51], v[36:39], off offset:512
	s_nop 1
	v_cvt_pk_bf16_f32 v36, v36, v37
	v_cvt_pk_bf16_f32 v37, v38, v39
	v_or_b32_e32 v38, 0x100, v46
	v_mov_b32_e32 v39, v47
	v_lshl_add_u64 v[38:39], s[56:57], 0, v[38:39]
	global_store_dwordx2 v[38:39], v[36:37], off
	global_store_dwordx4 v[50:51], v[32:35], off offset:576
	v_cvt_pk_bf16_f32 v36, v32, v33
	v_or_b32_e32 v46, 0x120, v46
	s_waitcnt lgkmcnt(0)
	v_add_f32_e32 v32, v40, v41
	ds_bpermute_b32 v33, v209, v32
	v_cvt_pk_bf16_f32 v37, v34, v35
	v_lshl_add_u64 v[34:35], s[56:57], 0, v[46:47]
	global_store_dwordx2 v[34:35], v[36:37], off
	s_and_saveexec_b64 s[26:27], s[4:5]
	s_cbranch_execz .LBB0_330
	v_lshl_add_u64 v[34:35], v[116:117], 2, s[18:19]
	s_waitcnt lgkmcnt(0)
	v_add_f32_e32 v32, v32, v33
	global_atomic_add_f32 v[34:35], v32, off
; __device__ __forceinline__ unsigned pk2(float lo, float hi) { const f32x2_t v = {lo, hi}; const bf16x2_t b = __builtin_convertvector(v, bf16x2_t); return __builtin_bit_cast(unsigned, b); }
;     __device__ __forceinline__ void operator()(const f32x4 (&acc)[2][2][4][2], const Unit& u, int wr, int wc, int fr, int fq) const {
;     ...
;         for (int ai = 0; ai < 2; ++ai) {
;             f32x4 bv[4][2][2];
; #pragma unroll
;             for (int m = 0; m < 4; ++m)
; #pragma unroll
;                 for (int bj = 0; bj < 2; ++bj)
; #pragma unroll
;                     for (int n = 0; n < 2; ++n) bv[m][bj][n] = *(const f32x4*)(base + (size_t)(row0 + ai * 128 + m * 16) * D + col0 + bj * 128 + n * 16);
;             asm volatile("" ::: "memory");
; #pragma unroll
;             for (int m = 0; m < 4; ++m) {
;                 const int row = row0 + ai * 128 + m * 16; float s = 0.f;
; #pragma unroll
;                 for (int bj = 0; bj < 2; ++bj)
; #pragma unroll
;                     for (int n = 0; n < 2; ++n) {
;                         const size_t off = (size_t)row * D + col0 + bj * 128 + n * 16;
;                         const f32x4 v = bv[m][bj][n] + acc[ai][bj][m][n] * alpha;
;                         *(f32x4*)(out + off) = v; s += (v[0] * v[0] + v[1] * v[1]) + (v[2] * v[2] + v[3] * v[3]);
;                         if (xb) { v2u w; w.x = pk2(v[0], v[1]); w.y = pk2(v[2], v[3]); *(v2u*)(xb + off) = w; }
;                     }
;                 s += __shfl_xor(s, 16); s += __shfl_xor(s, 32);
;                 if (fq == 0) atomicAdd(ss + row, s);
.LBB0_330:
	s_or_b64 exec, exec, s[26:27]
	s_waitcnt lgkmcnt(0)
	v_lshlrev_b64 v[32:33], 10, v[114:115]
	v_lshl_add_u64 v[32:33], v[32:33], 0, v[188:189]
	s_waitcnt vmcnt(31)
	v_pk_fma_f32 v[30:31], v[30:31], 0.5, v[94:95] op_sel_hi:[1,0,1]
	v_pk_fma_f32 v[28:29], v[28:29], 0.5, v[92:93] op_sel_hi:[1,0,1]
	v_lshl_add_u64 v[34:35], v[32:33], 2, s[14:15]
	v_mul_f32_e32 v36, v29, v29
	v_mul_f32_e32 v37, v31, v31
	global_store_dwordx4 v[34:35], v[28:31], off
	v_fmac_f32_e32 v36, v28, v28
	v_fmac_f32_e32 v37, v30, v30
	v_cvt_pk_bf16_f32 v28, v28, v29
	v_cvt_pk_bf16_f32 v29, v30, v31
	v_lshlrev_b64 v[30:31], 1, v[32:33]
	v_lshl_add_u64 v[32:33], s[56:57], 0, v[30:31]
	s_waitcnt vmcnt(31)
	v_pk_fma_f32 v[26:27], v[26:27], 0.5, v[90:91] op_sel_hi:[1,0,1]
	v_pk_fma_f32 v[24:25], v[24:25], 0.5, v[88:89] op_sel_hi:[1,0,1]
	global_store_dwordx2 v[32:33], v[28:29], off
	v_mul_f32_e32 v28, v25, v25
	v_mul_f32_e32 v29, v27, v27
	global_store_dwordx4 v[34:35], v[24:27], off offset:64
	v_fmac_f32_e32 v28, v24, v24
	v_fmac_f32_e32 v29, v26, v26
	v_cvt_pk_bf16_f32 v24, v24, v25
	v_cvt_pk_bf16_f32 v25, v26, v27
	v_or_b32_e32 v26, 32, v30
	v_mov_b32_e32 v27, v31
	v_lshl_add_u64 v[26:27], s[56:57], 0, v[26:27]
	s_waitcnt vmcnt(24)
	v_pk_fma_f32 v[22:23], v[22:23], 0.5, v[86:87] op_sel_hi:[1,0,1]
	v_pk_fma_f32 v[20:21], v[20:21], 0.5, v[84:85] op_sel_hi:[1,0,1]
	global_store_dwordx2 v[26:27], v[24:25], off
	v_mul_f32_e32 v24, v21, v21
	v_mul_f32_e32 v25, v23, v23
	v_fmac_f32_e32 v24, v20, v20
	v_fmac_f32_e32 v25, v22, v22
	s_waitcnt vmcnt(24)
	v_pk_fma_f32 v[18:19], v[18:19], 0.5, v[82:83] op_sel_hi:[1,0,1]
	v_pk_fma_f32 v[16:17], v[16:17], 0.5, v[80:81] op_sel_hi:[1,0,1]
	v_add_f32_e32 v36, v36, v37
	v_add_f32_e32 v28, v28, v29
	v_add_f32_e32 v24, v24, v25
	v_mul_f32_e32 v25, v17, v17
	v_mul_f32_e32 v26, v19, v19
	v_add_f32_e32 v28, v36, v28
	v_fmac_f32_e32 v25, v16, v16
	v_fmac_f32_e32 v26, v18, v18
	v_add_f32_e32 v24, v28, v24
	v_add_f32_e32 v25, v25, v26
	v_add_f32_e32 v24, v24, v25
	ds_bpermute_b32 v25, v210, v24
	global_store_dwordx4 v[34:35], v[20:23], off offset:512
	s_nop 1
	v_cvt_pk_bf16_f32 v20, v20, v21
	v_cvt_pk_bf16_f32 v21, v22, v23
	v_or_b32_e32 v22, 0x100, v30
	v_mov_b32_e32 v23, v31
	v_lshl_add_u64 v[22:23], s[56:57], 0, v[22:23]
	global_store_dwordx2 v[22:23], v[20:21], off
	global_store_dwordx4 v[34:35], v[16:19], off offset:576
	v_cvt_pk_bf16_f32 v20, v16, v17
	v_or_b32_e32 v30, 0x120, v30
	s_waitcnt lgkmcnt(0)
	v_add_f32_e32 v16, v24, v25
	ds_bpermute_b32 v17, v209, v16
	v_cvt_pk_bf16_f32 v21, v18, v19
	v_lshl_add_u64 v[18:19], s[56:57], 0, v[30:31]
	global_store_dwordx2 v[18:19], v[20:21], off
	s_and_saveexec_b64 s[26:27], s[4:5]
	s_cbranch_execz .LBB0_332
	v_lshl_add_u64 v[18:19], v[114:115], 2, s[18:19]
	s_waitcnt lgkmcnt(0)
	v_add_f32_e32 v16, v16, v17
	global_atomic_add_f32 v[18:19], v16, off
